# merged-phase K-loop + B1 fragment wait moved into MFMA segment + SGPR-base LDS-DMA addressing
# speedup vs baseline: 1.0230x; 1.0037x over previous
; #define PG8_STAGE(bufoff, gbase, voff) do { _Pragma("unroll") for (int _i = 0; _i < 2; ++_i) \
;         __builtin_amdgcn_global_load_lds((const unsigned*)((const char*)(gbase) + (voff)[_i]), (LAS unsigned*)(lds + (bufoff) + ldsw + _i * 8192), 16, 0, 0); } while (0)
; #define PG8_LDA(dst, b, h) do { _Pragma("unroll") for (int m = 0; m < 4; ++m) _Pragma("unroll") for (int k = 0; k < 2; ++k) dst[m][k] = *(const LAS bf16x8*)(lds + PG8_SA(b, h) + aoff + m * 2048 + k * 1024); } while (0)
; #define PG8_LDB(dst, b, h) do { _Pragma("unroll") for (int n = 0; n < 2; ++n) _Pragma("unroll") for (int k = 0; k < 2; ++k) dst[n][k] = *(const LAS bf16x8*)(lds + PG8_SB(b, h) + boff + n * 2048 + k * 1024); } while (0)
; #define PG8_MMA(ai, bj, At, Bt) do { __builtin_amdgcn_s_setprio(1); _Pragma("unroll") for (int m = 0; m < 4; ++m) _Pragma("unroll") for (int n = 0; n < 2; ++n) _Pragma("unroll") for (int k = 0; k < 2; ++k) \
;         acc[ai][bj][m][n] = __builtin_amdgcn_mfma_f32_16x16x32_bf16(Bt[n][k], At[m][k], acc[ai][bj][m][n], 0, 0, 0); __builtin_amdgcn_s_setprio(0); } while (0)
; #define PG8_WAIT_L(n) asm volatile("s_waitcnt lgkmcnt(" #n ")" ::: "memory")
; #define PG8_BAR __builtin_amdgcn_s_barrier()
; #define PG8_SCHED __builtin_amdgcn_sched_barrier(0)
; __device__ __forceinline__ void gemm_phase(LAS unsigned char* lds, const Gemm g, const StaticOrder& S, const Epi& E) {
;     ...
;         for (int t = 0; t < nt; t += 2) {
;             const bool last = (t == nt - 2);
;             const char* a1 = cA + (size_t)(t + 1) * kstep;
;             const char* a2 = last ? nA : cA + (size_t)(t + 2) * kstep; const char* b2 = last ? nB : cB + (size_t)(t + 2) * kstep;
;             const char* a3 = a2 + kstep; const char* b3 = b2 + kstep;
;             PG8_LDB(B0, 0, 0); PG8_SCHED; PG8_LDA(At, 0, 0); PG8_STAGE(PG8_SA(1, 1), a1 + hstep, voffA);
;             PG8_WAIT_L(8); PG8_BAR; PG8_WAIT_L(0); PG8_MMA(0, 0, At, B0); PG8_BAR; PG8_SCHED;
;             PG8_LDB(B1, 0, 1); PG8_STAGE(PG8_SB(0, 0), b2, voffB);
;             PG8_BAR; PG8_WAIT_L(0); PG8_MMA(0, 1, At, B1); PG8_BAR;
;             PG8_LDA(At, 0, 1); PG8_STAGE(PG8_SA(0, 0), a2, voffA);
;             PG8_BAR; PG8_WAIT_L(0); PG8_MMA(1, 0, At, B0); PG8_BAR; PG8_SCHED;
;             PG8_STAGE(PG8_SB(0, 1), b2 + hstep, voffB);
.LBB0_555:
	s_add_i32 s61, s54, 2
	s_add_u32 s56, s44, 0x80
	s_addc_u32 s55, s45, 0
	v_add_u32_e32 v142, 0x10000, v244
	v_add_u32_e32 v178, 0x14000, v244
	s_waitcnt lgkmcnt(0)
	ds_read_b128 v[130:133], v142
	ds_read_b128 v[134:137], v142 offset:1024
	ds_read_b128 v[138:141], v142 offset:2048
	ds_read_b128 v[142:145], v142 offset:3072
	s_cmp_eq_u32 s73, s54
	s_cselect_b32 s54, s28, s56
	s_cselect_b32 s55, s29, s55
	s_cselect_b32 s57, s47, s60
	s_cselect_b32 s56, s46, s59
	ds_read_b128 v[146:149], v245
	ds_read_b128 v[150:153], v245 offset:1024
	ds_read_b128 v[154:157], v245 offset:2048
	ds_read_b128 v[158:161], v245 offset:3072
	ds_read_b128 v[162:165], v245 offset:4096
	ds_read_b128 v[166:169], v245 offset:5120
	ds_read_b128 v[170:173], v245 offset:6144
	ds_read_b128 v[174:177], v245 offset:7168
	s_waitcnt lgkmcnt(8)
	ds_read_b128 v[202:205], v178
	ds_read_b128 v[206:209], v178 offset:1024
	ds_read_b128 v[210:213], v178 offset:2048
	ds_read_b128 v[214:217], v178 offset:3072
	s_add_u32 s86, s59, s48
	s_addc_u32 s87, s60, 0
	s_sub_u32 s86, s86, 0x80
	s_subb_u32 s87, s87, 0
	s_add_i32 m0, s65, 0x1c000
	s_nop 0
	global_load_lds_dwordx4 v182, s[86:87]
	s_add_i32 m0, s65, 0x1e000
	s_nop 0
	global_load_lds_dwordx4 v186, s[86:87]
	s_add_i32 m0, s66, 0xc000
	s_nop 0
	global_load_lds_dwordx4 v198, s[44:45]
	s_add_i32 m0, s66, 0xe000
	s_nop 0
	global_load_lds_dwordx4 v200, s[44:45]
	s_cmp_eq_u32 s61, 2
	s_cbranch_scc1 .Lmy_q10_first
	s_waitcnt vmcnt(8)
.Lmy_q10_first:
	s_waitcnt lgkmcnt(4)
	s_barrier
	s_setprio 1
	v_mfma_f32_16x16x32_bf16 v[126:129], v[130:133], v[146:149], v[126:129]
	v_mfma_f32_16x16x32_bf16 v[122:125], v[138:141], v[146:149], v[122:125]
	v_mfma_f32_16x16x32_bf16 v[118:121], v[130:133], v[154:157], v[118:121]
	v_mfma_f32_16x16x32_bf16 v[110:113], v[138:141], v[154:157], v[110:113]
	v_mfma_f32_16x16x32_bf16 v[102:105], v[130:133], v[162:165], v[102:105]
	v_mfma_f32_16x16x32_bf16 v[94:97], v[138:141], v[162:165], v[94:97]
	v_mfma_f32_16x16x32_bf16 v[86:89], v[130:133], v[170:173], v[86:89]
	v_mfma_f32_16x16x32_bf16 v[78:81], v[138:141], v[170:173], v[78:81]
	v_mfma_f32_16x16x32_bf16 v[126:129], v[134:137], v[150:153], v[126:129]
	v_mfma_f32_16x16x32_bf16 v[122:125], v[142:145], v[150:153], v[122:125]
	v_mfma_f32_16x16x32_bf16 v[118:121], v[134:137], v[158:161], v[118:121]
	v_mfma_f32_16x16x32_bf16 v[110:113], v[142:145], v[158:161], v[110:113]
	v_mfma_f32_16x16x32_bf16 v[102:105], v[134:137], v[166:169], v[102:105]
	v_mfma_f32_16x16x32_bf16 v[94:97], v[142:145], v[166:169], v[94:97]
	v_mfma_f32_16x16x32_bf16 v[86:89], v[134:137], v[174:177], v[86:89]
	v_mfma_f32_16x16x32_bf16 v[78:81], v[142:145], v[174:177], v[78:81]
	s_waitcnt lgkmcnt(0)
	v_mfma_f32_16x16x32_bf16 v[114:117], v[202:205], v[146:149], v[114:117]
	v_mfma_f32_16x16x32_bf16 v[106:109], v[210:213], v[146:149], v[106:109]
	v_mfma_f32_16x16x32_bf16 v[98:101], v[202:205], v[154:157], v[98:101]
	v_mfma_f32_16x16x32_bf16 v[90:93], v[210:213], v[154:157], v[90:93]
	v_mfma_f32_16x16x32_bf16 v[82:85], v[202:205], v[162:165], v[82:85]
	v_mfma_f32_16x16x32_bf16 v[74:77], v[210:213], v[162:165], v[74:77]
	v_mfma_f32_16x16x32_bf16 v[70:73], v[202:205], v[170:173], v[70:73]
	v_mfma_f32_16x16x32_bf16 v[66:69], v[210:213], v[170:173], v[66:69]
	v_mfma_f32_16x16x32_bf16 v[114:117], v[206:209], v[150:153], v[114:117]
	v_mfma_f32_16x16x32_bf16 v[106:109], v[214:217], v[150:153], v[106:109]
	v_mfma_f32_16x16x32_bf16 v[98:101], v[206:209], v[158:161], v[98:101]
	v_mfma_f32_16x16x32_bf16 v[90:93], v[214:217], v[158:161], v[90:93]
	v_mfma_f32_16x16x32_bf16 v[82:85], v[206:209], v[166:169], v[82:85]
	v_mfma_f32_16x16x32_bf16 v[74:77], v[214:217], v[166:169], v[74:77]
	v_mfma_f32_16x16x32_bf16 v[70:73], v[206:209], v[174:177], v[70:73]
	v_mfma_f32_16x16x32_bf16 v[66:69], v[214:217], v[174:177], v[66:69]
	s_setprio 0
	s_barrier
	ds_read_b128 v[146:149], v245 offset:16384
	ds_read_b128 v[150:153], v245 offset:17408
	ds_read_b128 v[154:157], v245 offset:18432
	ds_read_b128 v[158:161], v245 offset:19456
	ds_read_b128 v[162:165], v245 offset:20480
	ds_read_b128 v[166:169], v245 offset:21504
	ds_read_b128 v[170:173], v245 offset:22528
	ds_read_b128 v[174:177], v245 offset:23552
	s_add_u32 s86, s56, 0x80
	s_addc_u32 s87, s57, 0
	s_add_u32 s88, s54, 0x80
	s_addc_u32 s89, s55, 0
	s_add_i32 m0, s65, 0x10000
	s_nop 0
	global_load_lds_dwordx4 v182, s[56:57]
	s_add_i32 m0, s65, 0x12000
	s_nop 0
	global_load_lds_dwordx4 v186, s[56:57]
	s_mov_b32 m0, s66
	s_nop 0
	global_load_lds_dwordx4 v180, s[54:55]
	s_mov_b32 m0, s67
	s_nop 0
	global_load_lds_dwordx4 v184, s[54:55]
	s_waitcnt vmcnt(6) lgkmcnt(0)
	s_barrier
; #define PG8_STAGE(bufoff, gbase, voff) do { _Pragma("unroll") for (int _i = 0; _i < 2; ++_i) \
;         __builtin_amdgcn_global_load_lds((const unsigned*)((const char*)(gbase) + (voff)[_i]), (LAS unsigned*)(lds + (bufoff) + ldsw + _i * 8192), 16, 0, 0); } while (0)
; #define PG8_LDA(dst, b, h) do { _Pragma("unroll") for (int m = 0; m < 4; ++m) _Pragma("unroll") for (int k = 0; k < 2; ++k) dst[m][k] = *(const LAS bf16x8*)(lds + PG8_SA(b, h) + aoff + m * 2048 + k * 1024); } while (0)
; #define PG8_LDB(dst, b, h) do { _Pragma("unroll") for (int n = 0; n < 2; ++n) _Pragma("unroll") for (int k = 0; k < 2; ++k) dst[n][k] = *(const LAS bf16x8*)(lds + PG8_SB(b, h) + boff + n * 2048 + k * 1024); } while (0)
; #define PG8_MMA(ai, bj, At, Bt) do { __builtin_amdgcn_s_setprio(1); _Pragma("unroll") for (int m = 0; m < 4; ++m) _Pragma("unroll") for (int n = 0; n < 2; ++n) _Pragma("unroll") for (int k = 0; k < 2; ++k) \
;         acc[ai][bj][m][n] = __builtin_amdgcn_mfma_f32_16x16x32_bf16(Bt[n][k], At[m][k], acc[ai][bj][m][n], 0, 0, 0); __builtin_amdgcn_s_setprio(0); } while (0)
; #define PG8_WAIT_V(n) asm volatile("s_waitcnt vmcnt(" #n ")" ::: "memory")
; #define PG8_WAIT_L(n) asm volatile("s_waitcnt lgkmcnt(" #n ")" ::: "memory")
; #define PG8_BAR __builtin_amdgcn_s_barrier()
; #define PG8_SCHED __builtin_amdgcn_sched_barrier(0)
; __device__ __forceinline__ void gemm_phase(LAS unsigned char* lds, const Gemm g, const StaticOrder& S, const Epi& E) {
;     ...
;             PG8_BAR; PG8_WAIT_L(0); PG8_MMA(1, 0, At, B0); PG8_BAR; PG8_SCHED;
;             PG8_STAGE(PG8_SB(0, 1), b2 + hstep, voffB);
;             PG8_WAIT_V(6); PG8_BAR; PG8_MMA(1, 1, At, B1); PG8_BAR;
;             PG8_LDB(B0, 1, 0); PG8_SCHED; PG8_LDA(At, 1, 0); PG8_STAGE(PG8_SA(0, 1), a2 + hstep, voffA);
;             PG8_WAIT_L(8); PG8_BAR; PG8_WAIT_L(0); PG8_MMA(0, 0, At, B0); PG8_BAR; PG8_SCHED;
;             PG8_LDB(B1, 1, 1); PG8_STAGE(PG8_SB(1, 0), b3, voffB);
;             PG8_BAR; PG8_WAIT_L(0); PG8_MMA(0, 1, At, B1); PG8_BAR;
;             PG8_LDA(At, 1, 1); PG8_STAGE(PG8_SA(1, 0), a3, voffA);
;             PG8_BAR; PG8_WAIT_L(0); PG8_MMA(1, 0, At, B0); PG8_BAR; PG8_SCHED;
;             PG8_STAGE(PG8_SB(1, 1), b3 + hstep, voffB);
;             PG8_WAIT_V(6); PG8_BAR; PG8_MMA(1, 1, At, B1); PG8_BAR;
	s_setprio 1
	v_mfma_f32_16x16x32_bf16 v[62:65], v[130:133], v[146:149], v[62:65]
	v_mfma_f32_16x16x32_bf16 v[58:61], v[138:141], v[146:149], v[58:61]
	v_mfma_f32_16x16x32_bf16 v[54:57], v[130:133], v[154:157], v[54:57]
	v_mfma_f32_16x16x32_bf16 v[50:53], v[138:141], v[154:157], v[50:53]
	v_mfma_f32_16x16x32_bf16 v[38:41], v[130:133], v[162:165], v[38:41]
	v_mfma_f32_16x16x32_bf16 v[34:37], v[138:141], v[162:165], v[34:37]
	v_mfma_f32_16x16x32_bf16 v[22:25], v[130:133], v[170:173], v[22:25]
	v_mfma_f32_16x16x32_bf16 v[18:21], v[138:141], v[170:173], v[18:21]
	v_mfma_f32_16x16x32_bf16 v[62:65], v[134:137], v[150:153], v[62:65]
	v_mfma_f32_16x16x32_bf16 v[58:61], v[142:145], v[150:153], v[58:61]
	v_mfma_f32_16x16x32_bf16 v[54:57], v[134:137], v[158:161], v[54:57]
	v_mfma_f32_16x16x32_bf16 v[50:53], v[142:145], v[158:161], v[50:53]
	v_mfma_f32_16x16x32_bf16 v[38:41], v[134:137], v[166:169], v[38:41]
	v_mfma_f32_16x16x32_bf16 v[34:37], v[142:145], v[166:169], v[34:37]
	v_mfma_f32_16x16x32_bf16 v[22:25], v[134:137], v[174:177], v[22:25]
	v_mfma_f32_16x16x32_bf16 v[18:21], v[142:145], v[174:177], v[18:21]
	v_mfma_f32_16x16x32_bf16 v[46:49], v[202:205], v[146:149], v[46:49]
	v_mfma_f32_16x16x32_bf16 v[42:45], v[210:213], v[146:149], v[42:45]
	v_mfma_f32_16x16x32_bf16 v[30:33], v[202:205], v[154:157], v[30:33]
	v_mfma_f32_16x16x32_bf16 v[26:29], v[210:213], v[154:157], v[26:29]
	v_mfma_f32_16x16x32_bf16 v[14:17], v[202:205], v[162:165], v[14:17]
	v_mfma_f32_16x16x32_bf16 v[10:13], v[210:213], v[162:165], v[10:13]
	v_mfma_f32_16x16x32_bf16 v[6:9], v[202:205], v[170:173], v[6:9]
	v_mfma_f32_16x16x32_bf16 v[2:5], v[210:213], v[170:173], v[2:5]
	v_mfma_f32_16x16x32_bf16 v[46:49], v[206:209], v[150:153], v[46:49]
	v_mfma_f32_16x16x32_bf16 v[42:45], v[214:217], v[150:153], v[42:45]
	v_mfma_f32_16x16x32_bf16 v[30:33], v[206:209], v[158:161], v[30:33]
	v_mfma_f32_16x16x32_bf16 v[26:29], v[214:217], v[158:161], v[26:29]
	v_mfma_f32_16x16x32_bf16 v[14:17], v[206:209], v[166:169], v[14:17]
	v_mfma_f32_16x16x32_bf16 v[10:13], v[214:217], v[166:169], v[10:13]
	v_mfma_f32_16x16x32_bf16 v[6:9], v[206:209], v[174:177], v[6:9]
	v_mfma_f32_16x16x32_bf16 v[2:5], v[214:217], v[174:177], v[2:5]
	s_setprio 0
	s_barrier
	v_add_u32_e32 v142, 0x18000, v244
	v_add_u32_e32 v178, 0x1c000, v244
	ds_read_b128 v[130:133], v142
	ds_read_b128 v[134:137], v142 offset:1024
	ds_read_b128 v[138:141], v142 offset:2048
	ds_read_b128 v[142:145], v142 offset:3072
	ds_read_b128 v[146:149], v245 offset:32768
	ds_read_b128 v[150:153], v245 offset:33792
	ds_read_b128 v[154:157], v245 offset:34816
	ds_read_b128 v[158:161], v245 offset:35840
	ds_read_b128 v[162:165], v245 offset:36864
	ds_read_b128 v[166:169], v245 offset:37888
	ds_read_b128 v[170:173], v245 offset:38912
	ds_read_b128 v[174:177], v245 offset:39936
	s_waitcnt lgkmcnt(8)
	ds_read_b128 v[202:205], v178
	ds_read_b128 v[206:209], v178 offset:1024
	ds_read_b128 v[210:213], v178 offset:2048
	ds_read_b128 v[214:217], v178 offset:3072
	s_add_u32 s56, s56, s48
	s_addc_u32 s57, s57, 0
	s_add_u32 s54, s54, s48
	s_addc_u32 s55, s55, 0
	s_add_i32 m0, s65, 0x14000
	s_nop 0
	global_load_lds_dwordx4 v182, s[56:57]
	s_add_i32 m0, s65, 0x16000
	s_nop 0
	global_load_lds_dwordx4 v186, s[56:57]
	s_mov_b32 m0, s68
	s_nop 0
	global_load_lds_dwordx4 v180, s[54:55]
	s_mov_b32 m0, s69
	s_nop 0
	global_load_lds_dwordx4 v184, s[54:55]
	s_waitcnt vmcnt(8) lgkmcnt(4)
	s_barrier
	s_setprio 1
	v_mfma_f32_16x16x32_bf16 v[126:129], v[130:133], v[146:149], v[126:129]
	v_mfma_f32_16x16x32_bf16 v[122:125], v[138:141], v[146:149], v[122:125]
	v_mfma_f32_16x16x32_bf16 v[118:121], v[130:133], v[154:157], v[118:121]
	v_mfma_f32_16x16x32_bf16 v[110:113], v[138:141], v[154:157], v[110:113]
	v_mfma_f32_16x16x32_bf16 v[102:105], v[130:133], v[162:165], v[102:105]
	v_mfma_f32_16x16x32_bf16 v[94:97], v[138:141], v[162:165], v[94:97]
	v_mfma_f32_16x16x32_bf16 v[86:89], v[130:133], v[170:173], v[86:89]
	v_mfma_f32_16x16x32_bf16 v[78:81], v[138:141], v[170:173], v[78:81]
	v_mfma_f32_16x16x32_bf16 v[126:129], v[134:137], v[150:153], v[126:129]
	v_mfma_f32_16x16x32_bf16 v[122:125], v[142:145], v[150:153], v[122:125]
	v_mfma_f32_16x16x32_bf16 v[118:121], v[134:137], v[158:161], v[118:121]
	v_mfma_f32_16x16x32_bf16 v[110:113], v[142:145], v[158:161], v[110:113]
	v_mfma_f32_16x16x32_bf16 v[102:105], v[134:137], v[166:169], v[102:105]
	v_mfma_f32_16x16x32_bf16 v[94:97], v[142:145], v[166:169], v[94:97]
	v_mfma_f32_16x16x32_bf16 v[86:89], v[134:137], v[174:177], v[86:89]
	v_mfma_f32_16x16x32_bf16 v[78:81], v[142:145], v[174:177], v[78:81]
	s_waitcnt lgkmcnt(0)
	v_mfma_f32_16x16x32_bf16 v[114:117], v[202:205], v[146:149], v[114:117]
	v_mfma_f32_16x16x32_bf16 v[106:109], v[210:213], v[146:149], v[106:109]
	v_mfma_f32_16x16x32_bf16 v[98:101], v[202:205], v[154:157], v[98:101]
	v_mfma_f32_16x16x32_bf16 v[90:93], v[210:213], v[154:157], v[90:93]
	v_mfma_f32_16x16x32_bf16 v[82:85], v[202:205], v[162:165], v[82:85]
	v_mfma_f32_16x16x32_bf16 v[74:77], v[210:213], v[162:165], v[74:77]
	v_mfma_f32_16x16x32_bf16 v[70:73], v[202:205], v[170:173], v[70:73]
	v_mfma_f32_16x16x32_bf16 v[66:69], v[210:213], v[170:173], v[66:69]
	v_mfma_f32_16x16x32_bf16 v[114:117], v[206:209], v[150:153], v[114:117]
	v_mfma_f32_16x16x32_bf16 v[106:109], v[214:217], v[150:153], v[106:109]
	v_mfma_f32_16x16x32_bf16 v[98:101], v[206:209], v[158:161], v[98:101]
	v_mfma_f32_16x16x32_bf16 v[90:93], v[214:217], v[158:161], v[90:93]
	v_mfma_f32_16x16x32_bf16 v[82:85], v[206:209], v[166:169], v[82:85]
	v_mfma_f32_16x16x32_bf16 v[74:77], v[214:217], v[166:169], v[74:77]
	v_mfma_f32_16x16x32_bf16 v[70:73], v[206:209], v[174:177], v[70:73]
	v_mfma_f32_16x16x32_bf16 v[66:69], v[214:217], v[174:177], v[66:69]
	s_setprio 0
	s_barrier
	ds_read_b128 v[146:149], v245 offset:49152
	ds_read_b128 v[150:153], v245 offset:50176
	ds_read_b128 v[154:157], v245 offset:51200
	ds_read_b128 v[158:161], v245 offset:52224
	ds_read_b128 v[162:165], v245 offset:53248
	ds_read_b128 v[166:169], v245 offset:54272
	ds_read_b128 v[170:173], v245 offset:55296
	ds_read_b128 v[174:177], v245 offset:56320
	s_add_i32 m0, s65, 0x18000
	s_nop 0
	global_load_lds_dwordx4 v182, s[86:87]
	s_add_i32 m0, s65, 0x1a000
	s_nop 0
	global_load_lds_dwordx4 v186, s[86:87]
	s_mov_b32 m0, s70
	s_nop 0
	global_load_lds_dwordx4 v180, s[88:89]
	s_mov_b32 m0, s71
	s_nop 0
	global_load_lds_dwordx4 v184, s[88:89]
	s_cmp_ge_u32 s61, s72
	s_cbranch_scc1 .Lmy_q21_last
	s_waitcnt vmcnt(6)
	s_branch .Lmy_q21_cont
